# L0 down-proj residual epilogue rewritten: gate/LN params loaded once, X tile rows loaded in 3 batches instead of 57 serialized waits
# speedup vs baseline: 1.0383x; 1.0036x over previous
;     DI void operator()(const f32x4 (&acc)[2][2][4][2], const Unit& u, int wr, int wc, int fr, int fq) const {
;     ...
;         const float* g = gate + (size_t)s * 12288;
;         const float2* RS = (const float2*)(ws + WS_RSTAT);
; #pragma unroll
;         for (int ai = 0; ai < 2; ++ai)
; #pragma unroll
;             for (int m = 0; m < 4; ++m) {
;                 const int row = u.pm * BM + ai * HALF + wr * 64 + m * 16 + fr;
;                 float mu = 0.f, rs = 1.f;
;                 if (pg) { const float2 st = RS[row]; mu = st.x; rs = st.y; }
; #pragma unroll
;                 for (int bj = 0; bj < 2; ++bj)
; #pragma unroll
;                     for (int n = 0; n < 2; ++n) {
;                         const int col = u.pn * BM + bj * HALF + wc * 32 + n * 16 + 4 * fq;
;                         float* xp = X + (size_t)row * DM + col;
;                         f32x4 x4 = *(const f32x4*)xp; const f32x4 g4 = *(const f32x4*)(g + col);
;                         if (pg) x4 = (x4 - mu) * rs * *(const f32x4*)(pg + col) + *(const f32x4*)(pb + col);
;                         *(f32x4*)xp = x4 * ALPHA + g4 * acc[ai][bj][m][n];
.LBB0_1694:
	v_and_b32_e32 v197, 15, v202
	v_bfe_u32 v198, v202, 8, 1
	v_lshl_add_u32 v197, v198, 6, v197
	v_lshlrev_b32_e32 v159, 3, v197
	v_bfe_u32 v198, v202, 6, 2
	v_lshlrev_b32_e32 v157, 7, v198
	v_bfe_u32 v198, v202, 4, 2
	v_lshl_add_u32 v157, v198, 4, v157
	s_lshl_b32 s29, s3, 10
	v_add_u32_e32 v157, s29, v157
	v_lshl_add_u32 v161, v197, 13, v157
	v_add_u32_e32 v163, 0x20000, v161
	v_add_u32_e32 v165, 0x40000, v161
	v_add_u32_e32 v192, 0x60000, v161
	v_add_u32_e32 v193, 0x100000, v161
	v_add_u32_e32 v194, 0x120000, v161
	v_add_u32_e32 v195, 0x140000, v161
	v_add_u32_e32 v196, 0x160000, v161
	s_mov_b32 s89, 0x3fb504f3
	s_mul_i32 s29, s80, 57
	s_lshr_b32 s29, s29, 9
	s_mul_i32 s32, s29, 9
	s_cmp_lg_u32 s32, s80
	s_cselect_b32 s12, s29, 4
	s_mul_i32 s12, s12, 0xc000
	s_add_u32 s74, s50, 0x12000
	s_addc_u32 s75, s51, 0
	s_add_u32 s74, s74, s12
	s_addc_u32 s75, s75, 0
	global_load_dwordx4 v[222:225], v157, s[74:75] offset:0
	global_load_dwordx4 v[226:229], v157, s[74:75] offset:64
	global_load_dwordx4 v[230:233], v157, s[74:75] offset:512
	global_load_dwordx4 v[234:237], v157, s[74:75] offset:576
	s_add_u32 s74, s64, 0x0
	s_addc_u32 s75, s65, 0
	global_load_dwordx4 v[206:209], v157, s[74:75] offset:0
	global_load_dwordx4 v[210:213], v157, s[74:75] offset:64
	global_load_dwordx4 v[214:217], v157, s[74:75] offset:512
	global_load_dwordx4 v[218:221], v157, s[74:75] offset:576
	s_add_u32 s74, s66, 0x0
	s_addc_u32 s75, s67, 0
	global_load_dwordx4 v[238:241], v157, s[74:75] offset:0
	global_load_dwordx4 v[242:245], v157, s[74:75] offset:64
	global_load_dwordx4 v[246:249], v157, s[74:75] offset:512
	global_load_dwordx4 v[188:191], v157, s[74:75] offset:576
	s_lshl_b32 s29, s80, 11
	s_add_u32 s74, s50, 0x260a0000
	s_addc_u32 s75, s51, 0
	s_add_u32 s74, s74, s29
	s_addc_u32 s75, s75, 0
	global_load_dwordx2 v[128:129], v159, s[74:75] offset:0
	global_load_dwordx2 v[130:131], v159, s[74:75] offset:128
	global_load_dwordx2 v[132:133], v159, s[74:75] offset:256
	global_load_dwordx2 v[134:135], v159, s[74:75] offset:384
	global_load_dwordx2 v[136:137], v159, s[74:75] offset:1024
	global_load_dwordx2 v[138:139], v159, s[74:75] offset:1152
	global_load_dwordx2 v[140:141], v159, s[74:75] offset:1280
	global_load_dwordx2 v[142:143], v159, s[74:75] offset:1408
	s_lshl_b32 s29, s80, 21
	s_add_u32 s72, s50, 0xcba0000
	s_addc_u32 s73, s51, 0
	s_add_u32 s72, s72, s29
	s_addc_u32 s73, s73, 0
	s_waitcnt vmcnt(0)
	v_mul_f32_e32 v206, s89, v206
	v_mul_f32_e32 v238, s89, v238
	v_mul_f32_e32 v207, s89, v207
	v_mul_f32_e32 v239, s89, v239
	v_mul_f32_e32 v208, s89, v208
	v_mul_f32_e32 v240, s89, v240
	v_mul_f32_e32 v209, s89, v209
	v_mul_f32_e32 v241, s89, v241
	v_mul_f32_e32 v210, s89, v210
	v_mul_f32_e32 v242, s89, v242
	v_mul_f32_e32 v211, s89, v211
	v_mul_f32_e32 v243, s89, v243
	v_mul_f32_e32 v212, s89, v212
	v_mul_f32_e32 v244, s89, v244
	v_mul_f32_e32 v213, s89, v213
	v_mul_f32_e32 v245, s89, v245
	v_mul_f32_e32 v214, s89, v214
	v_mul_f32_e32 v246, s89, v246
	v_mul_f32_e32 v215, s89, v215
	v_mul_f32_e32 v247, s89, v247
	v_mul_f32_e32 v216, s89, v216
	v_mul_f32_e32 v248, s89, v248
	v_mul_f32_e32 v217, s89, v217
	v_mul_f32_e32 v249, s89, v249
	v_mul_f32_e32 v218, s89, v218
	v_mul_f32_e32 v188, s89, v188
	v_mul_f32_e32 v219, s89, v219
	v_mul_f32_e32 v189, s89, v189
	v_mul_f32_e32 v220, s89, v220
	v_mul_f32_e32 v190, s89, v190
	v_mul_f32_e32 v221, s89, v221
	v_mul_f32_e32 v191, s89, v191
	v_fma_f32 v124, v222, v124, v238
	v_fma_f32 v125, v223, v125, v239
	v_fma_f32 v126, v224, v126, v240
	v_fma_f32 v127, v225, v127, v241
	v_fma_f32 v120, v226, v120, v242
	v_fma_f32 v121, v227, v121, v243
	v_fma_f32 v122, v228, v122, v244
	v_fma_f32 v123, v229, v123, v245
	v_fma_f32 v104, v230, v104, v246
	v_fma_f32 v105, v231, v105, v247
	v_fma_f32 v106, v232, v106, v248
	v_fma_f32 v107, v233, v107, v249
	v_fma_f32 v96, v234, v96, v188
	v_fma_f32 v97, v235, v97, v189
	v_fma_f32 v98, v236, v98, v190
	v_fma_f32 v99, v237, v99, v191
	v_fma_f32 v116, v222, v116, v238
	v_fma_f32 v117, v223, v117, v239
	v_fma_f32 v118, v224, v118, v240
	v_fma_f32 v119, v225, v119, v241
	v_fma_f32 v112, v226, v112, v242
	v_fma_f32 v113, v227, v113, v243
	v_fma_f32 v114, v228, v114, v244
	v_fma_f32 v115, v229, v115, v245
	v_fma_f32 v88, v230, v88, v246
	v_fma_f32 v89, v231, v89, v247
	v_fma_f32 v90, v232, v90, v248
	v_fma_f32 v91, v233, v91, v249
	v_fma_f32 v80, v234, v80, v188
	v_fma_f32 v81, v235, v81, v189
	v_fma_f32 v82, v236, v82, v190
	v_fma_f32 v83, v237, v83, v191
	v_fma_f32 v108, v222, v108, v238
	v_fma_f32 v109, v223, v109, v239
	v_fma_f32 v110, v224, v110, v240
	v_fma_f32 v111, v225, v111, v241
	v_fma_f32 v100, v226, v100, v242
	v_fma_f32 v101, v227, v101, v243
	v_fma_f32 v102, v228, v102, v244
	v_fma_f32 v103, v229, v103, v245
	v_fma_f32 v76, v230, v76, v246
	v_fma_f32 v77, v231, v77, v247
	v_fma_f32 v78, v232, v78, v248
	v_fma_f32 v79, v233, v79, v249
	v_fma_f32 v72, v234, v72, v188
	v_fma_f32 v73, v235, v73, v189
	v_fma_f32 v74, v236, v74, v190
	v_fma_f32 v75, v237, v75, v191
	v_fma_f32 v92, v222, v92, v238
	v_fma_f32 v93, v223, v93, v239
	v_fma_f32 v94, v224, v94, v240
	v_fma_f32 v95, v225, v95, v241
	v_fma_f32 v84, v226, v84, v242
	v_fma_f32 v85, v227, v85, v243
	v_fma_f32 v86, v228, v86, v244
	v_fma_f32 v87, v229, v87, v245
	v_fma_f32 v68, v230, v68, v246
	v_fma_f32 v69, v231, v69, v247
	v_fma_f32 v70, v232, v70, v248
	v_fma_f32 v71, v233, v71, v249
	v_fma_f32 v64, v234, v64, v188
	v_fma_f32 v65, v235, v65, v189
	v_fma_f32 v66, v236, v66, v190
	v_fma_f32 v67, v237, v67, v191
	v_fma_f32 v60, v222, v60, v238
	v_fma_f32 v61, v223, v61, v239
	v_fma_f32 v62, v224, v62, v240
;     DI void operator()(const f32x4 (&acc)[2][2][4][2], const Unit& u, int wr, int wc, int fr, int fq) const {
;     ...
;                 const int row = u.pm * BM + ai * HALF + wr * 64 + m * 16 + fr;
;                 float mu = 0.f, rs = 1.f;
;                 if (pg) { const float2 st = RS[row]; mu = st.x; rs = st.y; }
; #pragma unroll
;                 for (int bj = 0; bj < 2; ++bj)
; #pragma unroll
;                     for (int n = 0; n < 2; ++n) {
;                         const int col = u.pn * BM + bj * HALF + wc * 32 + n * 16 + 4 * fq;
;                         float* xp = X + (size_t)row * DM + col;
;                         f32x4 x4 = *(const f32x4*)xp; const f32x4 g4 = *(const f32x4*)(g + col);
;                         if (pg) x4 = (x4 - mu) * rs * *(const f32x4*)(pg + col) + *(const f32x4*)(pb + col);
;                         *(f32x4*)xp = x4 * ALPHA + g4 * acc[ai][bj][m][n];
	v_fma_f32 v63, v225, v63, v241
	v_fma_f32 v56, v226, v56, v242
	v_fma_f32 v57, v227, v57, v243
	v_fma_f32 v58, v228, v58, v244
	v_fma_f32 v59, v229, v59, v245
	v_fma_f32 v40, v230, v40, v246
	v_fma_f32 v41, v231, v41, v247
	v_fma_f32 v42, v232, v42, v248
	v_fma_f32 v43, v233, v43, v249
	v_fma_f32 v32, v234, v32, v188
	v_fma_f32 v33, v235, v33, v189
	v_fma_f32 v34, v236, v34, v190
	v_fma_f32 v35, v237, v35, v191
	v_fma_f32 v52, v222, v52, v238
	v_fma_f32 v53, v223, v53, v239
	v_fma_f32 v54, v224, v54, v240
	v_fma_f32 v55, v225, v55, v241
	v_fma_f32 v48, v226, v48, v242
	v_fma_f32 v49, v227, v49, v243
	v_fma_f32 v50, v228, v50, v244
	v_fma_f32 v51, v229, v51, v245
	v_fma_f32 v24, v230, v24, v246
	v_fma_f32 v25, v231, v25, v247
	v_fma_f32 v26, v232, v26, v248
	v_fma_f32 v27, v233, v27, v249
	v_fma_f32 v16, v234, v16, v188
	v_fma_f32 v17, v235, v17, v189
	v_fma_f32 v18, v236, v18, v190
	v_fma_f32 v19, v237, v19, v191
	v_fma_f32 v44, v222, v44, v238
	v_fma_f32 v45, v223, v45, v239
	v_fma_f32 v46, v224, v46, v240
	v_fma_f32 v47, v225, v47, v241
	v_fma_f32 v36, v226, v36, v242
	v_fma_f32 v37, v227, v37, v243
	v_fma_f32 v38, v228, v38, v244
	v_fma_f32 v39, v229, v39, v245
	v_fma_f32 v12, v230, v12, v246
	v_fma_f32 v13, v231, v13, v247
	v_fma_f32 v14, v232, v14, v248
	v_fma_f32 v15, v233, v15, v249
	v_fma_f32 v8, v234, v8, v188
	v_fma_f32 v9, v235, v9, v189
	v_fma_f32 v10, v236, v10, v190
	v_fma_f32 v11, v237, v11, v191
	v_fma_f32 v28, v222, v28, v238
	v_fma_f32 v29, v223, v29, v239
	v_fma_f32 v30, v224, v30, v240
	v_fma_f32 v31, v225, v31, v241
	v_fma_f32 v20, v226, v20, v242
	v_fma_f32 v21, v227, v21, v243
	v_fma_f32 v22, v228, v22, v244
	v_fma_f32 v23, v229, v23, v245
	v_fma_f32 v4, v230, v4, v246
	v_fma_f32 v5, v231, v5, v247
	v_fma_f32 v6, v232, v6, v248
	v_fma_f32 v7, v233, v7, v249
	v_fma_f32 v0, v234, v0, v188
	v_fma_f32 v1, v235, v1, v189
	v_fma_f32 v2, v236, v2, v190
	v_fma_f32 v3, v237, v3, v191
	global_load_dwordx4 v[222:225], v161, s[72:73] offset:0
	global_load_dwordx4 v[226:229], v161, s[72:73] offset:64
	global_load_dwordx4 v[230:233], v161, s[72:73] offset:512
	global_load_dwordx4 v[234:237], v161, s[72:73] offset:576
	global_load_dwordx4 v[238:241], v163, s[72:73] offset:0
	global_load_dwordx4 v[242:245], v163, s[72:73] offset:64
	global_load_dwordx4 v[246:249], v163, s[72:73] offset:512
	global_load_dwordx4 v[188:191], v163, s[72:73] offset:576
	s_waitcnt vmcnt(0)
	v_sub_f32_e32 v222, v222, v128
	v_mul_f32_e32 v222, v222, v129
	v_fma_f32 v222, v222, v206, v124
	v_sub_f32_e32 v223, v223, v128
	v_mul_f32_e32 v223, v223, v129
	v_fma_f32 v223, v223, v207, v125
	v_sub_f32_e32 v224, v224, v128
	v_mul_f32_e32 v224, v224, v129
	v_fma_f32 v224, v224, v208, v126
	v_sub_f32_e32 v225, v225, v128
	v_mul_f32_e32 v225, v225, v129
	v_fma_f32 v225, v225, v209, v127
	v_sub_f32_e32 v226, v226, v128
	v_mul_f32_e32 v226, v226, v129
	v_fma_f32 v226, v226, v210, v120
	v_sub_f32_e32 v227, v227, v128
	v_mul_f32_e32 v227, v227, v129
	v_fma_f32 v227, v227, v211, v121
	v_sub_f32_e32 v228, v228, v128
	v_mul_f32_e32 v228, v228, v129
	v_fma_f32 v228, v228, v212, v122
	v_sub_f32_e32 v229, v229, v128
	v_mul_f32_e32 v229, v229, v129
	v_fma_f32 v229, v229, v213, v123
	v_sub_f32_e32 v230, v230, v128
	v_mul_f32_e32 v230, v230, v129
	v_fma_f32 v230, v230, v214, v104
	v_sub_f32_e32 v231, v231, v128
	v_mul_f32_e32 v231, v231, v129
	v_fma_f32 v231, v231, v215, v105
	v_sub_f32_e32 v232, v232, v128
	v_mul_f32_e32 v232, v232, v129
	v_fma_f32 v232, v232, v216, v106
	v_sub_f32_e32 v233, v233, v128
	v_mul_f32_e32 v233, v233, v129
	v_fma_f32 v233, v233, v217, v107
	v_sub_f32_e32 v234, v234, v128
	v_mul_f32_e32 v234, v234, v129
	v_fma_f32 v234, v234, v218, v96
	v_sub_f32_e32 v235, v235, v128
	v_mul_f32_e32 v235, v235, v129
	v_fma_f32 v235, v235, v219, v97
	v_sub_f32_e32 v236, v236, v128
	v_mul_f32_e32 v236, v236, v129
	v_fma_f32 v236, v236, v220, v98
	v_sub_f32_e32 v237, v237, v128
	v_mul_f32_e32 v237, v237, v129
	v_fma_f32 v237, v237, v221, v99
	v_sub_f32_e32 v238, v238, v130
	v_mul_f32_e32 v238, v238, v131
	v_fma_f32 v238, v238, v206, v116
	v_sub_f32_e32 v239, v239, v130
	v_mul_f32_e32 v239, v239, v131
	v_fma_f32 v239, v239, v207, v117
	v_sub_f32_e32 v240, v240, v130
	v_mul_f32_e32 v240, v240, v131
	v_fma_f32 v240, v240, v208, v118
	v_sub_f32_e32 v241, v241, v130
	v_mul_f32_e32 v241, v241, v131
	v_fma_f32 v241, v241, v209, v119
	v_sub_f32_e32 v242, v242, v130
	v_mul_f32_e32 v242, v242, v131
	v_fma_f32 v242, v242, v210, v112
	v_sub_f32_e32 v243, v243, v130
	v_mul_f32_e32 v243, v243, v131
	v_fma_f32 v243, v243, v211, v113
	v_sub_f32_e32 v244, v244, v130
	v_mul_f32_e32 v244, v244, v131
	v_fma_f32 v244, v244, v212, v114
	v_sub_f32_e32 v245, v245, v130
	v_mul_f32_e32 v245, v245, v131
	v_fma_f32 v245, v245, v213, v115
	v_sub_f32_e32 v246, v246, v130
	v_mul_f32_e32 v246, v246, v131
	v_fma_f32 v246, v246, v214, v88
	v_sub_f32_e32 v247, v247, v130
	v_mul_f32_e32 v247, v247, v131
	v_fma_f32 v247, v247, v215, v89
	v_sub_f32_e32 v248, v248, v130
	v_mul_f32_e32 v248, v248, v131
	v_fma_f32 v248, v248, v216, v90
	v_sub_f32_e32 v249, v249, v130
	v_mul_f32_e32 v249, v249, v131
	v_fma_f32 v249, v249, v217, v91
	v_sub_f32_e32 v188, v188, v130
	v_mul_f32_e32 v188, v188, v131
	v_fma_f32 v188, v188, v218, v80
	v_sub_f32_e32 v189, v189, v130
	v_mul_f32_e32 v189, v189, v131
	v_fma_f32 v189, v189, v219, v81
	v_sub_f32_e32 v190, v190, v130
	v_mul_f32_e32 v190, v190, v131
	v_fma_f32 v190, v190, v220, v82
	v_sub_f32_e32 v191, v191, v130
	v_mul_f32_e32 v191, v191, v131
	v_fma_f32 v191, v191, v221, v83
	global_load_dwordx4 v[124:127], v165, s[72:73] offset:0
	global_load_dwordx4 v[120:123], v165, s[72:73] offset:64
	global_load_dwordx4 v[104:107], v165, s[72:73] offset:512
	global_load_dwordx4 v[96:99], v165, s[72:73] offset:576
	global_load_dwordx4 v[116:119], v192, s[72:73] offset:0
	global_load_dwordx4 v[112:115], v192, s[72:73] offset:64
	global_load_dwordx4 v[88:91], v192, s[72:73] offset:512
	global_load_dwordx4 v[80:83], v192, s[72:73] offset:576
	global_store_dwordx4 v161, v[222:225], s[72:73] offset:0
	global_store_dwordx4 v161, v[226:229], s[72:73] offset:64
	global_store_dwordx4 v161, v[230:233], s[72:73] offset:512
	global_store_dwordx4 v161, v[234:237], s[72:73] offset:576
	global_store_dwordx4 v163, v[238:241], s[72:73] offset:0
	global_store_dwordx4 v163, v[242:245], s[72:73] offset:64
	global_store_dwordx4 v163, v[246:249], s[72:73] offset:512
	global_store_dwordx4 v163, v[188:191], s[72:73] offset:576
	global_load_dwordx4 v[222:225], v193, s[72:73] offset:0
	global_load_dwordx4 v[226:229], v193, s[72:73] offset:64
	global_load_dwordx4 v[230:233], v193, s[72:73] offset:512
	global_load_dwordx4 v[234:237], v193, s[72:73] offset:576
	global_load_dwordx4 v[238:241], v194, s[72:73] offset:0
	global_load_dwordx4 v[242:245], v194, s[72:73] offset:64
	global_load_dwordx4 v[246:249], v194, s[72:73] offset:512
	global_load_dwordx4 v[188:191], v194, s[72:73] offset:576
	s_waitcnt vmcnt(0)
;     DI void operator()(const f32x4 (&acc)[2][2][4][2], const Unit& u, int wr, int wc, int fr, int fq) const {
;     ...
;                 const int row = u.pm * BM + ai * HALF + wr * 64 + m * 16 + fr;
;                 float mu = 0.f, rs = 1.f;
;                 if (pg) { const float2 st = RS[row]; mu = st.x; rs = st.y; }
; #pragma unroll
;                 for (int bj = 0; bj < 2; ++bj)
; #pragma unroll
;                     for (int n = 0; n < 2; ++n) {
;                         const int col = u.pn * BM + bj * HALF + wc * 32 + n * 16 + 4 * fq;
;                         float* xp = X + (size_t)row * DM + col;
;                         f32x4 x4 = *(const f32x4*)xp; const f32x4 g4 = *(const f32x4*)(g + col);
;                         if (pg) x4 = (x4 - mu) * rs * *(const f32x4*)(pg + col) + *(const f32x4*)(pb + col);
;                         *(f32x4*)xp = x4 * ALPHA + g4 * acc[ai][bj][m][n];
	v_sub_f32_e32 v124, v124, v132
	v_mul_f32_e32 v124, v124, v133
	v_fma_f32 v124, v124, v206, v108
	v_sub_f32_e32 v125, v125, v132
	v_mul_f32_e32 v125, v125, v133
	v_fma_f32 v125, v125, v207, v109
	v_sub_f32_e32 v126, v126, v132
	v_mul_f32_e32 v126, v126, v133
	v_fma_f32 v126, v126, v208, v110
	v_sub_f32_e32 v127, v127, v132
	v_mul_f32_e32 v127, v127, v133
	v_fma_f32 v127, v127, v209, v111
	v_sub_f32_e32 v120, v120, v132
	v_mul_f32_e32 v120, v120, v133
	v_fma_f32 v120, v120, v210, v100
	v_sub_f32_e32 v121, v121, v132
	v_mul_f32_e32 v121, v121, v133
	v_fma_f32 v121, v121, v211, v101
	v_sub_f32_e32 v122, v122, v132
	v_mul_f32_e32 v122, v122, v133
	v_fma_f32 v122, v122, v212, v102
	v_sub_f32_e32 v123, v123, v132
	v_mul_f32_e32 v123, v123, v133
	v_fma_f32 v123, v123, v213, v103
	v_sub_f32_e32 v104, v104, v132
	v_mul_f32_e32 v104, v104, v133
	v_fma_f32 v104, v104, v214, v76
	v_sub_f32_e32 v105, v105, v132
	v_mul_f32_e32 v105, v105, v133
	v_fma_f32 v105, v105, v215, v77
	v_sub_f32_e32 v106, v106, v132
	v_mul_f32_e32 v106, v106, v133
	v_fma_f32 v106, v106, v216, v78
	v_sub_f32_e32 v107, v107, v132
	v_mul_f32_e32 v107, v107, v133
	v_fma_f32 v107, v107, v217, v79
	v_sub_f32_e32 v96, v96, v132
	v_mul_f32_e32 v96, v96, v133
	v_fma_f32 v96, v96, v218, v72
	v_sub_f32_e32 v97, v97, v132
	v_mul_f32_e32 v97, v97, v133
	v_fma_f32 v97, v97, v219, v73
	v_sub_f32_e32 v98, v98, v132
	v_mul_f32_e32 v98, v98, v133
	v_fma_f32 v98, v98, v220, v74
	v_sub_f32_e32 v99, v99, v132
	v_mul_f32_e32 v99, v99, v133
	v_fma_f32 v99, v99, v221, v75
	v_sub_f32_e32 v116, v116, v134
	v_mul_f32_e32 v116, v116, v135
	v_fma_f32 v116, v116, v206, v92
	v_sub_f32_e32 v117, v117, v134
	v_mul_f32_e32 v117, v117, v135
	v_fma_f32 v117, v117, v207, v93
	v_sub_f32_e32 v118, v118, v134
	v_mul_f32_e32 v118, v118, v135
	v_fma_f32 v118, v118, v208, v94
	v_sub_f32_e32 v119, v119, v134
	v_mul_f32_e32 v119, v119, v135
	v_fma_f32 v119, v119, v209, v95
	v_sub_f32_e32 v112, v112, v134
	v_mul_f32_e32 v112, v112, v135
	v_fma_f32 v112, v112, v210, v84
	v_sub_f32_e32 v113, v113, v134
	v_mul_f32_e32 v113, v113, v135
	v_fma_f32 v113, v113, v211, v85
	v_sub_f32_e32 v114, v114, v134
	v_mul_f32_e32 v114, v114, v135
	v_fma_f32 v114, v114, v212, v86
	v_sub_f32_e32 v115, v115, v134
	v_mul_f32_e32 v115, v115, v135
	v_fma_f32 v115, v115, v213, v87
	v_sub_f32_e32 v88, v88, v134
	v_mul_f32_e32 v88, v88, v135
	v_fma_f32 v88, v88, v214, v68
	v_sub_f32_e32 v89, v89, v134
	v_mul_f32_e32 v89, v89, v135
	v_fma_f32 v89, v89, v215, v69
	v_sub_f32_e32 v90, v90, v134
	v_mul_f32_e32 v90, v90, v135
	v_fma_f32 v90, v90, v216, v70
	v_sub_f32_e32 v91, v91, v134
	v_mul_f32_e32 v91, v91, v135
	v_fma_f32 v91, v91, v217, v71
	v_sub_f32_e32 v80, v80, v134
	v_mul_f32_e32 v80, v80, v135
	v_fma_f32 v80, v80, v218, v64
	v_sub_f32_e32 v81, v81, v134
	v_mul_f32_e32 v81, v81, v135
	v_fma_f32 v81, v81, v219, v65
	v_sub_f32_e32 v82, v82, v134
	v_mul_f32_e32 v82, v82, v135
	v_fma_f32 v82, v82, v220, v66
	v_sub_f32_e32 v83, v83, v134
	v_mul_f32_e32 v83, v83, v135
	v_fma_f32 v83, v83, v221, v67
	v_sub_f32_e32 v222, v222, v136
	v_mul_f32_e32 v222, v222, v137
	v_fma_f32 v222, v222, v206, v60
	v_sub_f32_e32 v223, v223, v136
	v_mul_f32_e32 v223, v223, v137
	v_fma_f32 v223, v223, v207, v61
	v_sub_f32_e32 v224, v224, v136
	v_mul_f32_e32 v224, v224, v137
	v_fma_f32 v224, v224, v208, v62
	v_sub_f32_e32 v225, v225, v136
	v_mul_f32_e32 v225, v225, v137
	v_fma_f32 v225, v225, v209, v63
	v_sub_f32_e32 v226, v226, v136
	v_mul_f32_e32 v226, v226, v137
	v_fma_f32 v226, v226, v210, v56
	v_sub_f32_e32 v227, v227, v136
	v_mul_f32_e32 v227, v227, v137
	v_fma_f32 v227, v227, v211, v57
	v_sub_f32_e32 v228, v228, v136
	v_mul_f32_e32 v228, v228, v137
	v_fma_f32 v228, v228, v212, v58
	v_sub_f32_e32 v229, v229, v136
	v_mul_f32_e32 v229, v229, v137
	v_fma_f32 v229, v229, v213, v59
	v_sub_f32_e32 v230, v230, v136
	v_mul_f32_e32 v230, v230, v137
	v_fma_f32 v230, v230, v214, v40
	v_sub_f32_e32 v231, v231, v136
	v_mul_f32_e32 v231, v231, v137
	v_fma_f32 v231, v231, v215, v41
	v_sub_f32_e32 v232, v232, v136
	v_mul_f32_e32 v232, v232, v137
	v_fma_f32 v232, v232, v216, v42
	v_sub_f32_e32 v233, v233, v136
	v_mul_f32_e32 v233, v233, v137
	v_fma_f32 v233, v233, v217, v43
	v_sub_f32_e32 v234, v234, v136
	v_mul_f32_e32 v234, v234, v137
	v_fma_f32 v234, v234, v218, v32
	v_sub_f32_e32 v235, v235, v136
	v_mul_f32_e32 v235, v235, v137
	v_fma_f32 v235, v235, v219, v33
	v_sub_f32_e32 v236, v236, v136
	v_mul_f32_e32 v236, v236, v137
	v_fma_f32 v236, v236, v220, v34
	v_sub_f32_e32 v237, v237, v136
	v_mul_f32_e32 v237, v237, v137
	v_fma_f32 v237, v237, v221, v35
	v_sub_f32_e32 v238, v238, v138
	v_mul_f32_e32 v238, v238, v139
	v_fma_f32 v238, v238, v206, v52
	v_sub_f32_e32 v239, v239, v138
	v_mul_f32_e32 v239, v239, v139
	v_fma_f32 v239, v239, v207, v53
	v_sub_f32_e32 v240, v240, v138
	v_mul_f32_e32 v240, v240, v139
	v_fma_f32 v240, v240, v208, v54
	v_sub_f32_e32 v241, v241, v138
	v_mul_f32_e32 v241, v241, v139
	v_fma_f32 v241, v241, v209, v55
	v_sub_f32_e32 v242, v242, v138
	v_mul_f32_e32 v242, v242, v139
	v_fma_f32 v242, v242, v210, v48
	v_sub_f32_e32 v243, v243, v138
	v_mul_f32_e32 v243, v243, v139
	v_fma_f32 v243, v243, v211, v49
	v_sub_f32_e32 v244, v244, v138
	v_mul_f32_e32 v244, v244, v139
	v_fma_f32 v244, v244, v212, v50
	v_sub_f32_e32 v245, v245, v138
	v_mul_f32_e32 v245, v245, v139
	v_fma_f32 v245, v245, v213, v51
	v_sub_f32_e32 v246, v246, v138
	v_mul_f32_e32 v246, v246, v139
	v_fma_f32 v246, v246, v214, v24
	v_sub_f32_e32 v247, v247, v138
;     DI void operator()(const f32x4 (&acc)[2][2][4][2], const Unit& u, int wr, int wc, int fr, int fq) const {
;     ...
;                 const int row = u.pm * BM + ai * HALF + wr * 64 + m * 16 + fr;
;                 float mu = 0.f, rs = 1.f;
;                 if (pg) { const float2 st = RS[row]; mu = st.x; rs = st.y; }
; #pragma unroll
;                 for (int bj = 0; bj < 2; ++bj)
; #pragma unroll
;                     for (int n = 0; n < 2; ++n) {
;                         const int col = u.pn * BM + bj * HALF + wc * 32 + n * 16 + 4 * fq;
;                         float* xp = X + (size_t)row * DM + col;
;                         f32x4 x4 = *(const f32x4*)xp; const f32x4 g4 = *(const f32x4*)(g + col);
;                         if (pg) x4 = (x4 - mu) * rs * *(const f32x4*)(pg + col) + *(const f32x4*)(pb + col);
;                         *(f32x4*)xp = x4 * ALPHA + g4 * acc[ai][bj][m][n];
	v_mul_f32_e32 v247, v247, v139
	v_fma_f32 v247, v247, v215, v25
	v_sub_f32_e32 v248, v248, v138
	v_mul_f32_e32 v248, v248, v139
	v_fma_f32 v248, v248, v216, v26
	v_sub_f32_e32 v249, v249, v138
	v_mul_f32_e32 v249, v249, v139
	v_fma_f32 v249, v249, v217, v27
	v_sub_f32_e32 v188, v188, v138
	v_mul_f32_e32 v188, v188, v139
	v_fma_f32 v188, v188, v218, v16
	v_sub_f32_e32 v189, v189, v138
	v_mul_f32_e32 v189, v189, v139
	v_fma_f32 v189, v189, v219, v17
	v_sub_f32_e32 v190, v190, v138
	v_mul_f32_e32 v190, v190, v139
	v_fma_f32 v190, v190, v220, v18
	v_sub_f32_e32 v191, v191, v138
	v_mul_f32_e32 v191, v191, v139
	v_fma_f32 v191, v191, v221, v19
	global_load_dwordx4 v[108:111], v195, s[72:73] offset:0
	global_load_dwordx4 v[100:103], v195, s[72:73] offset:64
	global_load_dwordx4 v[76:79], v195, s[72:73] offset:512
	global_load_dwordx4 v[72:75], v195, s[72:73] offset:576
	global_load_dwordx4 v[92:95], v196, s[72:73] offset:0
	global_load_dwordx4 v[84:87], v196, s[72:73] offset:64
	global_load_dwordx4 v[68:71], v196, s[72:73] offset:512
	global_load_dwordx4 v[64:67], v196, s[72:73] offset:576
	global_store_dwordx4 v165, v[124:127], s[72:73] offset:0
	global_store_dwordx4 v165, v[120:123], s[72:73] offset:64
	global_store_dwordx4 v165, v[104:107], s[72:73] offset:512
	global_store_dwordx4 v165, v[96:99], s[72:73] offset:576
	global_store_dwordx4 v192, v[116:119], s[72:73] offset:0
	global_store_dwordx4 v192, v[112:115], s[72:73] offset:64
	global_store_dwordx4 v192, v[88:91], s[72:73] offset:512
	global_store_dwordx4 v192, v[80:83], s[72:73] offset:576
	global_store_dwordx4 v193, v[222:225], s[72:73] offset:0
	global_store_dwordx4 v193, v[226:229], s[72:73] offset:64
	global_store_dwordx4 v193, v[230:233], s[72:73] offset:512
	global_store_dwordx4 v193, v[234:237], s[72:73] offset:576
	global_store_dwordx4 v194, v[238:241], s[72:73] offset:0
	global_store_dwordx4 v194, v[242:245], s[72:73] offset:64
	global_store_dwordx4 v194, v[246:249], s[72:73] offset:512
	global_store_dwordx4 v194, v[188:191], s[72:73] offset:576
	s_waitcnt vmcnt(16)
	v_sub_f32_e32 v108, v108, v140
	v_mul_f32_e32 v108, v108, v141
	v_fma_f32 v108, v108, v206, v44
	v_sub_f32_e32 v109, v109, v140
	v_mul_f32_e32 v109, v109, v141
	v_fma_f32 v109, v109, v207, v45
	v_sub_f32_e32 v110, v110, v140
	v_mul_f32_e32 v110, v110, v141
	v_fma_f32 v110, v110, v208, v46
	v_sub_f32_e32 v111, v111, v140
	v_mul_f32_e32 v111, v111, v141
	v_fma_f32 v111, v111, v209, v47
	v_sub_f32_e32 v100, v100, v140
	v_mul_f32_e32 v100, v100, v141
	v_fma_f32 v100, v100, v210, v36
	v_sub_f32_e32 v101, v101, v140
	v_mul_f32_e32 v101, v101, v141
	v_fma_f32 v101, v101, v211, v37
	v_sub_f32_e32 v102, v102, v140
	v_mul_f32_e32 v102, v102, v141
	v_fma_f32 v102, v102, v212, v38
	v_sub_f32_e32 v103, v103, v140
	v_mul_f32_e32 v103, v103, v141
	v_fma_f32 v103, v103, v213, v39
	v_sub_f32_e32 v76, v76, v140
	v_mul_f32_e32 v76, v76, v141
	v_fma_f32 v76, v76, v214, v12
	v_sub_f32_e32 v77, v77, v140
	v_mul_f32_e32 v77, v77, v141
	v_fma_f32 v77, v77, v215, v13
	v_sub_f32_e32 v78, v78, v140
	v_mul_f32_e32 v78, v78, v141
	v_fma_f32 v78, v78, v216, v14
	v_sub_f32_e32 v79, v79, v140
	v_mul_f32_e32 v79, v79, v141
	v_fma_f32 v79, v79, v217, v15
	v_sub_f32_e32 v72, v72, v140
	v_mul_f32_e32 v72, v72, v141
	v_fma_f32 v72, v72, v218, v8
	v_sub_f32_e32 v73, v73, v140
	v_mul_f32_e32 v73, v73, v141
	v_fma_f32 v73, v73, v219, v9
	v_sub_f32_e32 v74, v74, v140
	v_mul_f32_e32 v74, v74, v141
	v_fma_f32 v74, v74, v220, v10
	v_sub_f32_e32 v75, v75, v140
	v_mul_f32_e32 v75, v75, v141
	v_fma_f32 v75, v75, v221, v11
	v_sub_f32_e32 v92, v92, v142
	v_mul_f32_e32 v92, v92, v143
	v_fma_f32 v92, v92, v206, v28
	v_sub_f32_e32 v93, v93, v142
	v_mul_f32_e32 v93, v93, v143
	v_fma_f32 v93, v93, v207, v29
	v_sub_f32_e32 v94, v94, v142
	v_mul_f32_e32 v94, v94, v143
	v_fma_f32 v94, v94, v208, v30
	v_sub_f32_e32 v95, v95, v142
	v_mul_f32_e32 v95, v95, v143
	v_fma_f32 v95, v95, v209, v31
	v_sub_f32_e32 v84, v84, v142
	v_mul_f32_e32 v84, v84, v143
	v_fma_f32 v84, v84, v210, v20
	v_sub_f32_e32 v85, v85, v142
	v_mul_f32_e32 v85, v85, v143
	v_fma_f32 v85, v85, v211, v21
	v_sub_f32_e32 v86, v86, v142
	v_mul_f32_e32 v86, v86, v143
	v_fma_f32 v86, v86, v212, v22
	v_sub_f32_e32 v87, v87, v142
	v_mul_f32_e32 v87, v87, v143
	v_fma_f32 v87, v87, v213, v23
	v_sub_f32_e32 v68, v68, v142
	v_mul_f32_e32 v68, v68, v143
	v_fma_f32 v68, v68, v214, v4
	v_sub_f32_e32 v69, v69, v142
	v_mul_f32_e32 v69, v69, v143
	v_fma_f32 v69, v69, v215, v5
	v_sub_f32_e32 v70, v70, v142
	v_mul_f32_e32 v70, v70, v143
	v_fma_f32 v70, v70, v216, v6
	v_sub_f32_e32 v71, v71, v142
	v_mul_f32_e32 v71, v71, v143
	v_fma_f32 v71, v71, v217, v7
	v_sub_f32_e32 v64, v64, v142
	v_mul_f32_e32 v64, v64, v143
	v_fma_f32 v64, v64, v218, v0
	v_sub_f32_e32 v65, v65, v142
	v_mul_f32_e32 v65, v65, v143
	v_fma_f32 v65, v65, v219, v1
	v_sub_f32_e32 v66, v66, v142
	v_mul_f32_e32 v66, v66, v143
	v_fma_f32 v66, v66, v220, v2
	v_sub_f32_e32 v67, v67, v142
	v_mul_f32_e32 v67, v67, v143
	v_fma_f32 v67, v67, v221, v3
	global_store_dwordx4 v195, v[108:111], s[72:73] offset:0
	global_store_dwordx4 v195, v[100:103], s[72:73] offset:64
	global_store_dwordx4 v195, v[76:79], s[72:73] offset:512
	global_store_dwordx4 v195, v[72:75], s[72:73] offset:576
	global_store_dwordx4 v196, v[92:95], s[72:73] offset:0
	global_store_dwordx4 v196, v[84:87], s[72:73] offset:64
	global_store_dwordx4 v196, v[68:71], s[72:73] offset:512
	global_store_dwordx4 v196, v[64:67], s[72:73] offset:576
	s_branch .LBB0_1693
